# NSA selected branch: constant-bias tiles skip the accumulator register round-trip copies (38 v_mov_b64 + s_nop per tile)
# speedup vs baseline: 1.3489x; 1.0091x over previous
.LBB0_446:
	v_add3_u32 v0, s13, v198, v199
	v_add_u32_e32 v78, v0, v200
	v_add_u32_e32 v79, v0, v201
	s_waitcnt vmcnt(0)
	ds_read_b64_tr_b16 v[70:71], v78 offset:24576
	ds_read_b64_tr_b16 v[72:73], v78 offset:26624
	ds_read_b64_tr_b16 v[74:75], v79 offset:24576
	ds_read_b64_tr_b16 v[76:77], v79 offset:26624
	v_add_u32_e32 v80, v0, v202
	v_add_u32_e32 v0, v0, v203
	s_waitcnt lgkmcnt(0)
	v_mfma_f32_16x16x32_bf16 v[34:37], v[70:73], v[58:61], v[34:37]
	v_mfma_f32_16x16x32_bf16 v[30:33], v[70:73], v[66:69], v[30:33]
	ds_read_b64_tr_b16 v[70:71], v80 offset:24576
	ds_read_b64_tr_b16 v[72:73], v80 offset:26624
	v_mfma_f32_16x16x32_bf16 v[46:49], v[74:77], v[58:61], v[46:49]
	v_mfma_f32_16x16x32_bf16 v[26:29], v[74:77], v[66:69], v[26:29]
	ds_read_b64_tr_b16 v[74:75], v0 offset:24576
	ds_read_b64_tr_b16 v[76:77], v0 offset:26624
	s_waitcnt lgkmcnt(2)
	v_mfma_f32_16x16x32_bf16 v[42:45], v[70:73], v[58:61], v[42:45]
	v_mfma_f32_16x16x32_bf16 v[22:25], v[70:73], v[66:69], v[22:25]
	s_waitcnt lgkmcnt(0)
	v_mfma_f32_16x16x32_bf16 v[50:53], v[74:77], v[58:61], v[50:53]
	ds_read_b64_tr_b16 v[58:59], v78 offset:28672
	ds_read_b64_tr_b16 v[60:61], v78 offset:30720
	v_mfma_f32_16x16x32_bf16 v[18:21], v[74:77], v[66:69], v[18:21]
	ds_read_b64_tr_b16 v[66:67], v79 offset:28672
	ds_read_b64_tr_b16 v[68:69], v79 offset:30720
	s_waitcnt lgkmcnt(2)
	v_mfma_f32_16x16x32_bf16 v[34:37], v[58:61], v[54:57], v[34:37]
	v_mfma_f32_16x16x32_bf16 v[30:33], v[58:61], v[62:65], v[30:33]
	ds_read_b64_tr_b16 v[58:59], v80 offset:28672
	ds_read_b64_tr_b16 v[60:61], v80 offset:30720
	s_waitcnt lgkmcnt(2)
	v_mfma_f32_16x16x32_bf16 v[46:49], v[66:69], v[54:57], v[46:49]
	v_mfma_f32_16x16x32_bf16 v[26:29], v[66:69], v[62:65], v[26:29]
	ds_read_b64_tr_b16 v[66:67], v0 offset:28672
	ds_read_b64_tr_b16 v[68:69], v0 offset:30720
	s_waitcnt lgkmcnt(2)
	v_mfma_f32_16x16x32_bf16 v[42:45], v[58:61], v[54:57], v[42:45]
	v_mfma_f32_16x16x32_bf16 v[22:25], v[58:61], v[62:65], v[22:25]
	s_waitcnt lgkmcnt(0)
	v_mfma_f32_16x16x32_bf16 v[50:53], v[66:69], v[54:57], v[50:53]
	v_mfma_f32_16x16x32_bf16 v[18:21], v[66:69], v[62:65], v[18:21]
	s_branch .Lsel_fast
.LBB0_448:
	s_xor_b64 s[6:7], s[20:21], -1
	s_add_u32 s18, s8, -1
	s_addc_u32 s19, s9, -1
	v_mov_b64_e32 v[34:35], v[58:59]
	v_mov_b64_e32 v[46:47], v[66:67]
	v_mov_b64_e32 v[42:43], v[78:79]
	v_mov_b64_e32 v[50:51], v[54:55]
	v_mov_b64_e32 v[30:31], v[62:63]
	v_mov_b64_e32 v[26:27], v[74:75]
	v_mov_b64_e32 v[22:23], v[86:87]
	v_mov_b64_e32 v[18:19], v[70:71]
	s_and_b64 s[8:9], s[18:19], s[8:9]
	v_mov_b64_e32 v[160:161], v[166:167]
	v_mov_b64_e32 v[144:145], v[168:169]
	v_mov_b64_e32 v[36:37], v[60:61]
	v_mov_b64_e32 v[48:49], v[68:69]
	v_mov_b64_e32 v[44:45], v[80:81]
	v_mov_b64_e32 v[52:53], v[56:57]
	v_mov_b64_e32 v[32:33], v[64:65]
	v_mov_b64_e32 v[28:29], v[76:77]
	v_mov_b64_e32 v[24:25], v[88:89]
	v_mov_b64_e32 v[20:21], v[72:73]
	s_mov_b32 s13, 1
	s_mov_b64 s[20:21], 0
	s_and_b64 vcc, exec, s[6:7]
	s_cbranch_vccz .LBB0_419
	s_branch .LBB0_449
.Lsel_fast:
	s_xor_b64 s[6:7], s[20:21], -1
	s_add_u32 s18, s8, -1
	s_addc_u32 s19, s9, -1
	s_and_b64 s[8:9], s[18:19], s[8:9]
	s_mov_b32 s13, 1
	s_mov_b64 s[20:21], 0
	s_and_b64 vcc, exec, s[6:7]
	s_cbranch_vccz .LBB0_419
	s_nop 7
